# grid barriers: non-leader workgroups wait on the cross-XCD arrival counter reaching (gen+1)*nx (release seen one round trip earlier)
# baseline (speedup 1.0000x reference)
; __device__ __forceinline__ unsigned xb_ld(unsigned* p)              { return __hip_atomic_load(p, __ATOMIC_RELAXED, __HIP_MEMORY_SCOPE_AGENT); }
; __device__ __forceinline__ unsigned xb_add(unsigned* p, unsigned v) { return __hip_atomic_fetch_add(p, v, __ATOMIC_RELAXED, __HIP_MEMORY_SCOPE_AGENT); }
; #define XB_SPIN(cond, bar) do { unsigned _sp = 0; while (cond) { __builtin_amdgcn_s_sleep(1); \
;     if ((++_sp & 255u) == 0u) { if (xb_ld(&(bar)[XB_TMO])) break; if (_sp > XB_SPIN_CAP) { atomicAdd(&(bar)[XB_TMO], 1u); break; } } } } while (0)
; __device__ __forceinline__ void xcd_barrier(const XcdBarrier& b) {
;     ...
;         const unsigned old = xb_add(&bar[XB_XSUB(b.x)], 1u);
;         const unsigned gen = old / nloc;
;         if (old + 1u == (gen + 1u) * nloc) {
;             __builtin_amdgcn_fence(__ATOMIC_RELEASE, "agent");
;             asm volatile("s_waitcnt vmcnt(0)" ::: "memory");
;             const unsigned og = xb_add(&bar[XB_TOP], 1u);
;             const unsigned tg = og / nx;
;             if (og + 1u == (tg + 1u) * nx) xb_add(&bar[XB_TOPGEN], 1u);
;             else XB_SPIN(xb_ld(&bar[XB_TOPGEN]) == tg, bar);
;             __builtin_amdgcn_fence(__ATOMIC_ACQUIRE, "agent");
;             xb_add(&bar[XB_XGEN(b.x)], 1u);
;             asm volatile("s_waitcnt vmcnt(0)" ::: "memory");
;         } else {
;             XB_SPIN(xb_ld(&bar[XB_XGEN(b.x)]) == gen, bar);
.LBB0_216:
	s_lshl_b32 s0, s39, 8
	s_add_u32 s0, s38, s0
	s_addc_u32 s1, s37, 0
	v_mov_b32_e32 v1, s0
	v_add_co_u32_e32 v4, vcc, 0x101000, v1
	v_mov_b32_e32 v1, s1
	s_nop 0
	v_addc_co_u32_e32 v5, vcc, 0, v1, vcc
	v_mov_b32_e32 v1, 1
	flat_atomic_add v1, v[4:5], v1 offset:1024 sc0
	v_cvt_f32_u32_e32 v3, v2
	v_sub_u32_e32 v4, 0, v2
	s_add_u32 s27, s0, 0x100000
	s_addc_u32 s26, s1, 0
	v_rcp_iflag_f32_e32 v3, v3
	s_nop 0
	v_mul_f32_e32 v3, 0x4f7ffffe, v3
	v_cvt_u32_f32_e32 v3, v3
	v_mul_lo_u32 v4, v4, v3
	v_mul_hi_u32 v4, v3, v4
	v_add_u32_e32 v3, v3, v4
	s_waitcnt vmcnt(0) lgkmcnt(0)
	v_mul_hi_u32 v3, v1, v3
	v_mul_lo_u32 v5, v3, v2
	v_add_u32_e32 v4, 1, v1
	v_sub_u32_e32 v1, v1, v5
	v_add_u32_e32 v6, 1, v3
	v_cmp_ge_u32_e32 vcc, v1, v2
	v_sub_u32_e32 v5, v1, v2
	s_nop 0
	v_cndmask_b32_e32 v3, v3, v6, vcc
	v_cndmask_b32_e32 v1, v1, v5, vcc
	v_add_u32_e32 v5, 1, v3
	v_cmp_ge_u32_e32 vcc, v1, v2
	s_nop 1
	v_cndmask_b32_e32 v1, v3, v5, vcc
	v_mad_u64_u32 v[2:3], s[0:1], v2, v1, v[2:3]
	v_cmp_ne_u32_e32 vcc, v4, v2
	s_and_saveexec_b64 s[0:1], vcc
	s_xor_b64 s[0:1], exec, s[0:1]
	s_cbranch_execz .LBB0_229
	v_mad_u32_u24 v1, v1, v0, v0
	v_mov_b32_e32 v0, s27
	v_add_co_u32_e32 v2, vcc, 0x2000, v0
	v_mov_b32_e32 v0, s26
	s_nop 0
	v_addc_co_u32_e32 v3, vcc, 0, v0, vcc
	s_add_u32 s8, s38, 0x103400
	s_addc_u32 s9, s37, 0
	v_mov_b64_e32 v[2:3], s[8:9]
	flat_load_dword v0, v[2:3] sc1
	s_waitcnt vmcnt(0) lgkmcnt(0)
	v_cmp_lt_u32_e32 vcc, v0, v1
	s_and_saveexec_b64 s[4:5], vcc
	s_cbranch_execz .LBB0_228
	s_add_u32 s6, s38, 0x100200
	s_addc_u32 s7, s37, 0
	s_mov_b32 s28, 1
	s_mov_b64 s[10:11], 0
	s_branch .LBB0_220

; __device__ __forceinline__ unsigned xb_ld(unsigned* p)              { return __hip_atomic_load(p, __ATOMIC_RELAXED, __HIP_MEMORY_SCOPE_AGENT); }
; #define XB_SPIN(cond, bar) do { unsigned _sp = 0; while (cond) { __builtin_amdgcn_s_sleep(1); \
;     if ((++_sp & 255u) == 0u) { if (xb_ld(&(bar)[XB_TMO])) break; if (_sp > XB_SPIN_CAP) { atomicAdd(&(bar)[XB_TMO], 1u); break; } } } } while (0)
; __device__ __forceinline__ void xcd_barrier(const XcdBarrier& b) {
;     ...
;             XB_SPIN(xb_ld(&bar[XB_XGEN(b.x)]) == gen, bar);
.LBB0_224:
	s_andn2_b64 s[16:17], s[16:17], exec
	s_and_b64 s[22:23], s[22:23], exec
	s_or_b64 s[16:17], s[16:17], s[22:23]
	s_and_saveexec_b64 s[22:23], s[20:21]
	s_cbranch_execz .LBB0_219
	v_mov_b64_e32 v[2:3], s[8:9]
	flat_load_dword v0, v[2:3] sc1
	s_add_i32 s28, s28, 1
	s_or_b64 s[16:17], s[16:17], exec
	s_waitcnt vmcnt(0) lgkmcnt(0)
	v_cmp_ge_u32_e32 vcc, v0, v1
	s_orn2_b64 s[18:19], vcc, exec
	s_branch .LBB0_219

; __device__ __forceinline__ unsigned xb_ld(unsigned* p)              { return __hip_atomic_load(p, __ATOMIC_RELAXED, __HIP_MEMORY_SCOPE_AGENT); }
; __device__ __forceinline__ unsigned xb_add(unsigned* p, unsigned v) { return __hip_atomic_fetch_add(p, v, __ATOMIC_RELAXED, __HIP_MEMORY_SCOPE_AGENT); }
; #define XB_SPIN(cond, bar) do { unsigned _sp = 0; while (cond) { __builtin_amdgcn_s_sleep(1); \
;     if ((++_sp & 255u) == 0u) { if (xb_ld(&(bar)[XB_TMO])) break; if (_sp > XB_SPIN_CAP) { atomicAdd(&(bar)[XB_TMO], 1u); break; } } } } while (0)
; __device__ __forceinline__ void xcd_barrier(const XcdBarrier& b) {
;     ...
;         const unsigned old = xb_add(&bar[XB_XSUB(b.x)], 1u);
;         const unsigned gen = old / nloc;
;         if (old + 1u == (gen + 1u) * nloc) {
;             __builtin_amdgcn_fence(__ATOMIC_RELEASE, "agent");
;             asm volatile("s_waitcnt vmcnt(0)" ::: "memory");
;             const unsigned og = xb_add(&bar[XB_TOP], 1u);
;             const unsigned tg = og / nx;
;             if (og + 1u == (tg + 1u) * nx) xb_add(&bar[XB_TOPGEN], 1u);
;             else XB_SPIN(xb_ld(&bar[XB_TOPGEN]) == tg, bar);
;             __builtin_amdgcn_fence(__ATOMIC_ACQUIRE, "agent");
;             xb_add(&bar[XB_XGEN(b.x)], 1u);
;             asm volatile("s_waitcnt vmcnt(0)" ::: "memory");
;         } else {
;             XB_SPIN(xb_ld(&bar[XB_XGEN(b.x)]) == gen, bar);
.LBB0_629:
	s_lshl_b32 s0, s40, 8
	s_add_u32 s0, s39, s0
	s_addc_u32 s1, s38, 0
	v_mov_b32_e32 v1, s0
	v_add_co_u32_e32 v4, vcc, 0x101000, v1
	v_mov_b32_e32 v1, s1
	s_nop 0
	v_addc_co_u32_e32 v5, vcc, 0, v1, vcc
	v_mov_b32_e32 v1, 1
	flat_atomic_add v1, v[4:5], v1 offset:1024 sc0
	v_cvt_f32_u32_e32 v3, v2
	v_sub_u32_e32 v4, 0, v2
	s_add_u32 s27, s0, 0x100000
	s_addc_u32 s26, s1, 0
	v_rcp_iflag_f32_e32 v3, v3
	s_nop 0
	v_mul_f32_e32 v3, 0x4f7ffffe, v3
	v_cvt_u32_f32_e32 v3, v3
	v_mul_lo_u32 v4, v4, v3
	v_mul_hi_u32 v4, v3, v4
	v_add_u32_e32 v3, v3, v4
	s_waitcnt vmcnt(0) lgkmcnt(0)
	v_mul_hi_u32 v3, v1, v3
	v_mul_lo_u32 v5, v3, v2
	v_add_u32_e32 v4, 1, v1
	v_sub_u32_e32 v1, v1, v5
	v_add_u32_e32 v6, 1, v3
	v_cmp_ge_u32_e32 vcc, v1, v2
	v_sub_u32_e32 v5, v1, v2
	s_nop 0
	v_cndmask_b32_e32 v3, v3, v6, vcc
	v_cndmask_b32_e32 v1, v1, v5, vcc
	v_add_u32_e32 v5, 1, v3
	v_cmp_ge_u32_e32 vcc, v1, v2
	s_nop 1
	v_cndmask_b32_e32 v1, v3, v5, vcc
	v_mad_u64_u32 v[2:3], s[0:1], v2, v1, v[2:3]
	v_cmp_ne_u32_e32 vcc, v4, v2
	s_and_saveexec_b64 s[0:1], vcc
	s_xor_b64 s[0:1], exec, s[0:1]
	s_cbranch_execz .LBB0_642
	v_mad_u32_u24 v1, v1, v0, v0
	v_mov_b32_e32 v0, s27
	v_add_co_u32_e32 v2, vcc, 0x2000, v0
	v_mov_b32_e32 v0, s26
	s_nop 0
	v_addc_co_u32_e32 v3, vcc, 0, v0, vcc
	s_add_u32 s8, s39, 0x103400
	s_addc_u32 s9, s38, 0
	v_mov_b64_e32 v[2:3], s[8:9]
	flat_load_dword v0, v[2:3] sc1
	s_waitcnt vmcnt(0) lgkmcnt(0)
	v_cmp_lt_u32_e32 vcc, v0, v1
	s_and_saveexec_b64 s[4:5], vcc
	s_cbranch_execz .LBB0_641
	s_add_u32 s6, s39, 0x100200
	s_addc_u32 s7, s38, 0
	s_mov_b32 s28, 1
	s_mov_b64 s[10:11], 0
	s_branch .LBB0_633

; __device__ __forceinline__ unsigned xb_ld(unsigned* p)              { return __hip_atomic_load(p, __ATOMIC_RELAXED, __HIP_MEMORY_SCOPE_AGENT); }
; __device__ __forceinline__ unsigned xb_add(unsigned* p, unsigned v) { return __hip_atomic_fetch_add(p, v, __ATOMIC_RELAXED, __HIP_MEMORY_SCOPE_AGENT); }
; #define XB_SPIN(cond, bar) do { unsigned _sp = 0; while (cond) { __builtin_amdgcn_s_sleep(1); \
;     if ((++_sp & 255u) == 0u) { if (xb_ld(&(bar)[XB_TMO])) break; if (_sp > XB_SPIN_CAP) { atomicAdd(&(bar)[XB_TMO], 1u); break; } } } } while (0)
; __device__ __forceinline__ void xcd_barrier(const XcdBarrier& b) {
;     ...
;         const unsigned old = xb_add(&bar[XB_XSUB(b.x)], 1u);
;         const unsigned gen = old / nloc;
;         if (old + 1u == (gen + 1u) * nloc) {
;             __builtin_amdgcn_fence(__ATOMIC_RELEASE, "agent");
;             asm volatile("s_waitcnt vmcnt(0)" ::: "memory");
;             const unsigned og = xb_add(&bar[XB_TOP], 1u);
;             const unsigned tg = og / nx;
;             if (og + 1u == (tg + 1u) * nx) xb_add(&bar[XB_TOPGEN], 1u);
;             else XB_SPIN(xb_ld(&bar[XB_TOPGEN]) == tg, bar);
;             __builtin_amdgcn_fence(__ATOMIC_ACQUIRE, "agent");
;             xb_add(&bar[XB_XGEN(b.x)], 1u);
;             asm volatile("s_waitcnt vmcnt(0)" ::: "memory");
;         } else {
;             XB_SPIN(xb_ld(&bar[XB_XGEN(b.x)]) == gen, bar);
.LBB0_696:
	s_lshl_b32 s0, s42, 8
	s_add_u32 s0, s39, s0
	s_addc_u32 s1, s38, 0
	v_mov_b32_e32 v1, s0
	v_add_co_u32_e32 v4, vcc, 0x101000, v1
	v_mov_b32_e32 v1, s1
	s_nop 0
	v_addc_co_u32_e32 v5, vcc, 0, v1, vcc
	v_mov_b32_e32 v1, 1
	flat_atomic_add v1, v[4:5], v1 offset:1024 sc0
	v_cvt_f32_u32_e32 v3, v2
	v_sub_u32_e32 v4, 0, v2
	s_add_u32 s27, s0, 0x100000
	s_addc_u32 s26, s1, 0
	v_rcp_iflag_f32_e32 v3, v3
	s_nop 0
	v_mul_f32_e32 v3, 0x4f7ffffe, v3
	v_cvt_u32_f32_e32 v3, v3
	v_mul_lo_u32 v4, v4, v3
	v_mul_hi_u32 v4, v3, v4
	v_add_u32_e32 v3, v3, v4
	s_waitcnt vmcnt(0) lgkmcnt(0)
	v_mul_hi_u32 v3, v1, v3
	v_mul_lo_u32 v5, v3, v2
	v_add_u32_e32 v4, 1, v1
	v_sub_u32_e32 v1, v1, v5
	v_add_u32_e32 v6, 1, v3
	v_cmp_ge_u32_e32 vcc, v1, v2
	v_sub_u32_e32 v5, v1, v2
	s_nop 0
	v_cndmask_b32_e32 v3, v3, v6, vcc
	v_cndmask_b32_e32 v1, v1, v5, vcc
	v_add_u32_e32 v5, 1, v3
	v_cmp_ge_u32_e32 vcc, v1, v2
	s_nop 1
	v_cndmask_b32_e32 v1, v3, v5, vcc
	v_mad_u64_u32 v[2:3], s[0:1], v2, v1, v[2:3]
	v_cmp_ne_u32_e32 vcc, v4, v2
	s_and_saveexec_b64 s[0:1], vcc
	s_xor_b64 s[0:1], exec, s[0:1]
	s_cbranch_execz .LBB0_709
	v_mad_u32_u24 v1, v1, v0, v0
	v_mov_b32_e32 v0, s27
	v_add_co_u32_e32 v2, vcc, 0x2000, v0
	v_mov_b32_e32 v0, s26
	s_nop 0
	v_addc_co_u32_e32 v3, vcc, 0, v0, vcc
	s_add_u32 s8, s39, 0x103400
	s_addc_u32 s9, s38, 0
	v_mov_b64_e32 v[2:3], s[8:9]
	flat_load_dword v0, v[2:3] sc1
	s_waitcnt vmcnt(0) lgkmcnt(0)
	v_cmp_lt_u32_e32 vcc, v0, v1
	s_and_saveexec_b64 s[4:5], vcc
	s_cbranch_execz .LBB0_708
	s_add_u32 s6, s39, 0x100200
	s_addc_u32 s7, s38, 0
	s_mov_b32 s28, 1
	s_mov_b64 s[10:11], 0
	s_branch .LBB0_700

; __device__ __forceinline__ unsigned xb_ld(unsigned* p)              { return __hip_atomic_load(p, __ATOMIC_RELAXED, __HIP_MEMORY_SCOPE_AGENT); }
; __device__ __forceinline__ unsigned xb_add(unsigned* p, unsigned v) { return __hip_atomic_fetch_add(p, v, __ATOMIC_RELAXED, __HIP_MEMORY_SCOPE_AGENT); }
; #define XB_SPIN(cond, bar) do { unsigned _sp = 0; while (cond) { __builtin_amdgcn_s_sleep(1); \
;     if ((++_sp & 255u) == 0u) { if (xb_ld(&(bar)[XB_TMO])) break; if (_sp > XB_SPIN_CAP) { atomicAdd(&(bar)[XB_TMO], 1u); break; } } } } while (0)
; __device__ __forceinline__ void xcd_barrier(const XcdBarrier& b) {
;     ...
;         const unsigned old = xb_add(&bar[XB_XSUB(b.x)], 1u);
;         const unsigned gen = old / nloc;
;         if (old + 1u == (gen + 1u) * nloc) {
;             __builtin_amdgcn_fence(__ATOMIC_RELEASE, "agent");
;             asm volatile("s_waitcnt vmcnt(0)" ::: "memory");
;             const unsigned og = xb_add(&bar[XB_TOP], 1u);
;             const unsigned tg = og / nx;
;             if (og + 1u == (tg + 1u) * nx) xb_add(&bar[XB_TOPGEN], 1u);
;             else XB_SPIN(xb_ld(&bar[XB_TOPGEN]) == tg, bar);
;             __builtin_amdgcn_fence(__ATOMIC_ACQUIRE, "agent");
;             xb_add(&bar[XB_XGEN(b.x)], 1u);
;             asm volatile("s_waitcnt vmcnt(0)" ::: "memory");
;         } else {
;             XB_SPIN(xb_ld(&bar[XB_XGEN(b.x)]) == gen, bar);
.LBB0_786:
	s_lshl_b32 s0, s42, 8
	s_add_u32 s0, s39, s0
	s_addc_u32 s1, s38, 0
	v_mov_b32_e32 v1, s0
	v_add_co_u32_e32 v4, vcc, 0x101000, v1
	v_mov_b32_e32 v1, s1
	s_nop 0
	v_addc_co_u32_e32 v5, vcc, 0, v1, vcc
	v_mov_b32_e32 v1, 1
	flat_atomic_add v1, v[4:5], v1 offset:1024 sc0
	v_cvt_f32_u32_e32 v3, v2
	v_sub_u32_e32 v4, 0, v2
	s_add_u32 s29, s0, 0x100000
	s_addc_u32 s28, s1, 0
	v_rcp_iflag_f32_e32 v3, v3
	s_nop 0
	v_mul_f32_e32 v3, 0x4f7ffffe, v3
	v_cvt_u32_f32_e32 v3, v3
	v_mul_lo_u32 v4, v4, v3
	v_mul_hi_u32 v4, v3, v4
	v_add_u32_e32 v3, v3, v4
	s_waitcnt vmcnt(0) lgkmcnt(0)
	v_mul_hi_u32 v3, v1, v3
	v_mul_lo_u32 v5, v3, v2
	v_add_u32_e32 v4, 1, v1
	v_sub_u32_e32 v1, v1, v5
	v_add_u32_e32 v6, 1, v3
	v_cmp_ge_u32_e32 vcc, v1, v2
	v_sub_u32_e32 v5, v1, v2
	s_nop 0
	v_cndmask_b32_e32 v3, v3, v6, vcc
	v_cndmask_b32_e32 v1, v1, v5, vcc
	v_add_u32_e32 v5, 1, v3
	v_cmp_ge_u32_e32 vcc, v1, v2
	s_nop 1
	v_cndmask_b32_e32 v1, v3, v5, vcc
	v_mad_u64_u32 v[2:3], s[0:1], v2, v1, v[2:3]
	v_cmp_ne_u32_e32 vcc, v4, v2
	s_and_saveexec_b64 s[0:1], vcc
	s_xor_b64 s[0:1], exec, s[0:1]
	s_cbranch_execz .LBB0_799
	v_mad_u32_u24 v1, v1, v0, v0
	v_mov_b32_e32 v0, s29
	v_add_co_u32_e32 v2, vcc, 0x2000, v0
	v_mov_b32_e32 v0, s28
	s_nop 0
	v_addc_co_u32_e32 v3, vcc, 0, v0, vcc
	s_add_u32 s10, s39, 0x103400
	s_addc_u32 s11, s38, 0
	v_mov_b64_e32 v[2:3], s[10:11]
	flat_load_dword v0, v[2:3] sc1
	s_waitcnt vmcnt(0) lgkmcnt(0)
	v_cmp_lt_u32_e32 vcc, v0, v1
	s_and_saveexec_b64 s[6:7], vcc
	s_cbranch_execz .LBB0_798
	s_add_u32 s8, s39, 0x100200
	s_addc_u32 s9, s38, 0
	s_mov_b32 s30, 1
	s_mov_b64 s[12:13], 0
	s_branch .LBB0_790

; __device__ __forceinline__ unsigned xb_ld(unsigned* p)              { return __hip_atomic_load(p, __ATOMIC_RELAXED, __HIP_MEMORY_SCOPE_AGENT); }
; #define XB_SPIN(cond, bar) do { unsigned _sp = 0; while (cond) { __builtin_amdgcn_s_sleep(1); \
;     if ((++_sp & 255u) == 0u) { if (xb_ld(&(bar)[XB_TMO])) break; if (_sp > XB_SPIN_CAP) { atomicAdd(&(bar)[XB_TMO], 1u); break; } } } } while (0)
; __device__ __forceinline__ void xcd_barrier(const XcdBarrier& b) {
;     ...
;             XB_SPIN(xb_ld(&bar[XB_XGEN(b.x)]) == gen, bar);
.LBB0_794:
	s_andn2_b64 s[18:19], s[18:19], exec
	s_and_b64 s[24:25], s[24:25], exec
	s_or_b64 s[18:19], s[18:19], s[24:25]
	s_and_saveexec_b64 s[24:25], s[22:23]
	s_cbranch_execz .LBB0_789
	v_mov_b64_e32 v[2:3], s[10:11]
	flat_load_dword v0, v[2:3] sc1
	s_add_i32 s30, s30, 1
	s_or_b64 s[18:19], s[18:19], exec
	s_waitcnt vmcnt(0) lgkmcnt(0)
	v_cmp_ge_u32_e32 vcc, v0, v1
	s_orn2_b64 s[20:21], vcc, exec
	s_branch .LBB0_789

; __device__ __forceinline__ unsigned xb_ld(unsigned* p)              { return __hip_atomic_load(p, __ATOMIC_RELAXED, __HIP_MEMORY_SCOPE_AGENT); }
; __device__ __forceinline__ unsigned xb_add(unsigned* p, unsigned v) { return __hip_atomic_fetch_add(p, v, __ATOMIC_RELAXED, __HIP_MEMORY_SCOPE_AGENT); }
; #define XB_SPIN(cond, bar) do { unsigned _sp = 0; while (cond) { __builtin_amdgcn_s_sleep(1); \
;     if ((++_sp & 255u) == 0u) { if (xb_ld(&(bar)[XB_TMO])) break; if (_sp > XB_SPIN_CAP) { atomicAdd(&(bar)[XB_TMO], 1u); break; } } } } while (0)
; __device__ __forceinline__ void xcd_barrier(const XcdBarrier& b) {
;     ...
;         const unsigned old = xb_add(&bar[XB_XSUB(b.x)], 1u);
;         const unsigned gen = old / nloc;
;         if (old + 1u == (gen + 1u) * nloc) {
;             __builtin_amdgcn_fence(__ATOMIC_RELEASE, "agent");
;             asm volatile("s_waitcnt vmcnt(0)" ::: "memory");
;             const unsigned og = xb_add(&bar[XB_TOP], 1u);
;             const unsigned tg = og / nx;
;             if (og + 1u == (tg + 1u) * nx) xb_add(&bar[XB_TOPGEN], 1u);
;             else XB_SPIN(xb_ld(&bar[XB_TOPGEN]) == tg, bar);
;             __builtin_amdgcn_fence(__ATOMIC_ACQUIRE, "agent");
;             xb_add(&bar[XB_XGEN(b.x)], 1u);
;             asm volatile("s_waitcnt vmcnt(0)" ::: "memory");
;         } else {
;             XB_SPIN(xb_ld(&bar[XB_XGEN(b.x)]) == gen, bar);
.LBB0_851:
	s_lshl_b32 s0, s42, 8
	s_add_u32 s0, s41, s0
	s_addc_u32 s1, s40, 0
	v_mov_b32_e32 v1, s0
	v_add_co_u32_e32 v4, vcc, 0x101000, v1
	v_mov_b32_e32 v1, s1
	s_nop 0
	v_addc_co_u32_e32 v5, vcc, 0, v1, vcc
	v_mov_b32_e32 v1, 1
	flat_atomic_add v1, v[4:5], v1 offset:1024 sc0
	v_cvt_f32_u32_e32 v3, v2
	v_sub_u32_e32 v4, 0, v2
	s_add_u32 s29, s0, 0x100000
	s_addc_u32 s28, s1, 0
	v_rcp_iflag_f32_e32 v3, v3
	s_nop 0
	v_mul_f32_e32 v3, 0x4f7ffffe, v3
	v_cvt_u32_f32_e32 v3, v3
	v_mul_lo_u32 v4, v4, v3
	v_mul_hi_u32 v4, v3, v4
	v_add_u32_e32 v3, v3, v4
	s_waitcnt vmcnt(0) lgkmcnt(0)
	v_mul_hi_u32 v3, v1, v3
	v_mul_lo_u32 v5, v3, v2
	v_add_u32_e32 v4, 1, v1
	v_sub_u32_e32 v1, v1, v5
	v_add_u32_e32 v6, 1, v3
	v_cmp_ge_u32_e32 vcc, v1, v2
	v_sub_u32_e32 v5, v1, v2
	s_nop 0
	v_cndmask_b32_e32 v3, v3, v6, vcc
	v_cndmask_b32_e32 v1, v1, v5, vcc
	v_add_u32_e32 v5, 1, v3
	v_cmp_ge_u32_e32 vcc, v1, v2
	s_nop 1
	v_cndmask_b32_e32 v1, v3, v5, vcc
	v_mad_u64_u32 v[2:3], s[0:1], v2, v1, v[2:3]
	v_cmp_ne_u32_e32 vcc, v4, v2
	s_and_saveexec_b64 s[0:1], vcc
	s_xor_b64 s[0:1], exec, s[0:1]
	s_cbranch_execz .LBB0_864
	v_mad_u32_u24 v1, v1, v0, v0
	v_mov_b32_e32 v0, s29
	v_add_co_u32_e32 v2, vcc, 0x2000, v0
	v_mov_b32_e32 v0, s28
	s_nop 0
	v_addc_co_u32_e32 v3, vcc, 0, v0, vcc
	s_add_u32 s10, s41, 0x103400
	s_addc_u32 s11, s40, 0
	v_mov_b64_e32 v[2:3], s[10:11]
	flat_load_dword v0, v[2:3] sc1
	s_waitcnt vmcnt(0) lgkmcnt(0)
	v_cmp_lt_u32_e32 vcc, v0, v1
	s_and_saveexec_b64 s[6:7], vcc
	s_cbranch_execz .LBB0_863
	s_add_u32 s8, s41, 0x100200
	s_addc_u32 s9, s40, 0
	s_mov_b32 s30, 1
	s_mov_b64 s[12:13], 0
	s_branch .LBB0_855
